# MoBA loops v3: next-tile K fragments prefetched in softmax segment, V reads + next C-in in MFMA gaps, fall-through layout, s_setprio 1 around the 16-MFMA segment
# speedup vs baseline: 1.0169x; 1.0169x over previous
.LBB0_1058:
	s_nop 8
	v_exp_f32_e32 v56, v32
	s_nop 0
	v_exp_f32_e32 v57, v16
	v_exp_f32_e32 v112, v33
	v_exp_f32_e32 v16, v17
	v_exp_f32_e32 v58, v18
	v_add_f32_e32 v17, v57, v56
	v_exp_f32_e32 v18, v19
	v_pk_add_f32 v[32:33], v[16:17], v[112:113]
	v_exp_f32_e32 v17, v34
	v_pk_add_f32 v[32:33], v[32:33], v[32:33] op_sel_hi:[0,1]
	v_exp_f32_e32 v32, v35
	v_lshlrev_b32_e32 v59, 1, v52
	v_add_f32_e32 v19, v58, v17
	s_mov_b64 s[8:9], 0x80000
	v_pk_add_f32 v[34:35], v[18:19], v[32:33]
	v_exp_f32_e32 v19, v36
	v_pk_add_f32 v[34:35], v[34:35], v[34:35] op_sel_hi:[0,1]
	v_exp_f32_e32 v33, v20
	v_exp_f32_e32 v34, v37
	v_exp_f32_e32 v20, v21
	v_lshl_add_u64 v[114:115], v[48:49], 0, s[8:9]
	v_add_f32_e32 v21, v33, v19
	s_add_i32 s8, s86, s42
	v_pk_add_f32 v[36:37], v[20:21], v[34:35]
	v_exp_f32_e32 v21, v38
	v_pk_add_f32 v[36:37], v[36:37], v[36:37] op_sel_hi:[0,1]
	v_exp_f32_e32 v35, v22
	v_exp_f32_e32 v36, v39
	v_exp_f32_e32 v22, v23
	v_cvt_pk_bf16_f32 v100, v57, v16
	v_add_f32_e32 v23, v35, v21
	s_waitcnt vmcnt(0) lgkmcnt(0)
	s_barrier
	v_pk_add_f32 v[38:39], v[22:23], v[36:37]
	v_exp_f32_e32 v23, v40
	v_pk_add_f32 v[38:39], v[38:39], v[38:39] op_sel_hi:[0,1]
	v_exp_f32_e32 v37, v24
	v_exp_f32_e32 v38, v41
	v_exp_f32_e32 v24, v25
	v_and_b32_e32 v25, 32, v59
	v_add_u32_e32 v59, s89, v25
	v_add_f32_e32 v25, v37, v23
	v_pk_add_f32 v[40:41], v[24:25], v[38:39]
	v_exp_f32_e32 v25, v42
	v_pk_add_f32 v[40:41], v[40:41], v[40:41] op_sel_hi:[0,1]
	v_exp_f32_e32 v39, v26
	v_exp_f32_e32 v40, v43
	v_exp_f32_e32 v26, v27
	v_lshrrev_b32_e32 v27, 2, v52
	v_and_or_b32 v52, v27, 3, v55
	v_add_f32_e32 v27, v39, v25
	v_pk_add_f32 v[42:43], v[26:27], v[40:41]
	v_exp_f32_e32 v27, v44
	v_pk_add_f32 v[42:43], v[42:43], v[42:43] op_sel_hi:[0,1]
	v_exp_f32_e32 v41, v28
	v_exp_f32_e32 v42, v45
	v_exp_f32_e32 v28, v29
	v_add_u32_e32 v16, s8, v54
	v_add_f32_e32 v29, v41, v27
	s_lshl_b32 s30, s91, 2
	v_pk_add_f32 v[44:45], v[28:29], v[42:43]
	v_exp_f32_e32 v29, v46
	v_pk_add_f32 v[44:45], v[44:45], v[44:45] op_sel_hi:[0,1]
	v_exp_f32_e32 v43, v30
	v_exp_f32_e32 v44, v47
	v_exp_f32_e32 v30, v31
	v_lshlrev_b32_e32 v52, 6, v52
	v_add_f32_e32 v31, v43, v29
	v_cvt_pk_bf16_f32 v108, v56, v112
	v_pk_add_f32 v[46:47], v[30:31], v[44:45]
	v_sub_u32_e32 v112, v16, v55
	v_add_f32_e32 v31, v46, v47
	v_mov_b32_e32 v16, 0
	s_add_i32 s31, s30, -2
	s_mov_b32 s34, 1
	s_add_i32 s35, s30, 4
	v_add3_u32 v132, v59, v53, v52
	s_mov_b32 s44, 0
	v_add_f32_e32 v131, 0, v31
	v_cvt_pk_bf16_f32 v109, v17, v32
	v_cvt_pk_bf16_f32 v110, v19, v34
	v_cvt_pk_bf16_f32 v111, v21, v36
	v_cvt_pk_bf16_f32 v104, v23, v38
	v_cvt_pk_bf16_f32 v105, v25, v40
	v_cvt_pk_bf16_f32 v106, v27, v42
	v_cvt_pk_bf16_f32 v107, v29, v44
	v_cvt_pk_bf16_f32 v101, v58, v18
	v_cvt_pk_bf16_f32 v102, v33, v20
	v_cvt_pk_bf16_f32 v103, v35, v22
	v_cvt_pk_bf16_f32 v96, v37, v24
	v_cvt_pk_bf16_f32 v97, v39, v26
	v_cvt_pk_bf16_f32 v98, v41, v28
	v_cvt_pk_bf16_f32 v99, v43, v30
	s_or_b32 s36, s30, 2
	v_lshl_add_u64 v[116:117], v[50:51], 0, s[26:27]
	v_mov_b32_e32 v17, v16
	v_mov_b32_e32 v18, v16
	v_mov_b32_e32 v19, v16
	v_mov_b32_e32 v20, v16
	v_mov_b32_e32 v21, v16
	v_mov_b32_e32 v22, v16
	v_mov_b32_e32 v23, v16
	v_mov_b32_e32 v24, v16
	v_mov_b32_e32 v25, v16
	v_mov_b32_e32 v26, v16
	v_mov_b32_e32 v27, v16
	v_mov_b32_e32 v28, v16
	v_mov_b32_e32 v29, v16
	v_mov_b32_e32 v30, v16
	v_mov_b32_e32 v31, v16
	v_mov_b32_e32 v32, v16
	v_mov_b32_e32 v33, v16
	v_mov_b32_e32 v34, v16
	v_mov_b32_e32 v35, v16
	v_mov_b32_e32 v36, v16
	v_mov_b32_e32 v37, v16
	v_mov_b32_e32 v38, v16
	v_mov_b32_e32 v39, v16
	v_mov_b32_e32 v40, v16
	v_mov_b32_e32 v41, v16
	v_mov_b32_e32 v42, v16
	v_mov_b32_e32 v43, v16
	v_mov_b32_e32 v44, v16
	v_mov_b32_e32 v45, v16
	v_mov_b32_e32 v46, v16
	v_mov_b32_e32 v47, v16
	s_add_i32 s42, s44, 0x2000
	s_and_b32 s45, s42, 0x6000
	v_add_u32_e32 v133, s45, v130
	ds_read_b128 v[154:157], v133
	ds_read_b128 v[158:161], v133 offset:512
	ds_read_b128 v[162:165], v133 offset:2048
	ds_read_b128 v[166:169], v133 offset:2560
	ds_read_b128 v[170:173], v133 offset:4096
	ds_read_b128 v[174:177], v133 offset:4608
	ds_read_b128 v[178:181], v133 offset:6144
	ds_read_b128 v[182:185], v133 offset:6656
	s_lshr_b32 s45, s34, 2
	v_lshrrev_b32_e32 v219, s45, v129
	v_and_b32_e32 v219, 1, v219
	v_cmp_eq_u32_e32 vcc, 1, v219
	s_cmp_ge_i32 s34, s31
	s_nop 0
	v_cndmask_b32_e32 v219, v126, v128, vcc
	s_cselect_b64 vcc, 0, -1
	s_nop 1
	v_cndmask_b32_e32 v219, 0, v219, vcc
	v_add_f32_e32 v220, v0, v219
	v_add_f32_e32 v221, v1, v219
	v_add_f32_e32 v222, v2, v219
	v_add_f32_e32 v223, v3, v219
	v_add_f32_e32 v224, v4, v219
	v_add_f32_e32 v225, v5, v219
	v_add_f32_e32 v226, v6, v219
	v_add_f32_e32 v227, v7, v219
	v_add_f32_e32 v228, v8, v219
	v_add_f32_e32 v229, v9, v219
	v_add_f32_e32 v230, v10, v219
	v_add_f32_e32 v231, v11, v219
	v_add_f32_e32 v232, v12, v219
	v_add_f32_e32 v233, v13, v219
	v_add_f32_e32 v234, v14, v219
	v_add_f32_e32 v235, v15, v219
	s_add_i32 s37, s34, -1
	s_cmp_ge_u32 s37, s30
	s_mov_b32 s43, 0
	s_cbranch_scc1 .LBB0_1060

; #define ATT_LAS __attribute__((address_space(3)))
; #define ATT_MFMA(a, b, c) __builtin_amdgcn_mfma_f32_32x32x16_bf16((a), (b), (c), 0, 0, 0)
; __device__ __forceinline__ void qkt(f32x16& p0, f32x16& p1, lds_cptr kb, const bf16x8* qr, const f32x16& z) {
; #pragma unroll
;     for (int d0 = 0; d0 < 4; ++d0) {
;         const bf16x8 b0 = *(const ATT_LAS bf16x8*)(kb + d0 * 2048);
;         const bf16x8 b1 = *(const ATT_LAS bf16x8*)(kb + d0 * 2048 + 512);
;         if (d0 == 0) { p0 = ATT_MFMA(b0, qr[0], z); p1 = ATT_MFMA(b1, qr[0], z); }
;         else { p0 = ATT_MFMA(b0, qr[d0], p0); p1 = ATT_MFMA(b1, qr[d0], p1); } }
; }
; __device__ __forceinline__ void pv(f32x16* o, int vb, bf16x8 pa0, bf16x8 pa1, bf16x8 pa2, bf16x8 pa3) {
; #pragma unroll
;     for (int d0 = 0; d0 < 2; ++d0) { s16x4 lo[4], hi[4];
; #pragma unroll
;         for (int ks = 0; ks < 4; ++ks) {
;             asm volatile("ds_read_b64_tr_b16 %0,%1 offset:%c2" : "=&v"(lo[ks]) : "v"(vb), "i"(d0 * 4096 + ks * 1024) : "memory");
;             asm volatile("ds_read_b64_tr_b16 %0,%1 offset:%c2" : "=&v"(hi[ks]) : "v"(vb), "i"(d0 * 4096 + ks * 1024 + 512) : "memory"); }
;         asm volatile("s_waitcnt lgkmcnt(0)" ::: "memory"); __builtin_amdgcn_sched_barrier(0);
;     ...
;         o[d0] = ATT_MFMA(pa0, ATT_PK(0), o[d0]);
;         o[d0] = ATT_MFMA(pa1, ATT_PK(1), o[d0]);
;         o[d0] = ATT_MFMA(pa2, ATT_PK(2), o[d0]);
;         o[d0] = ATT_MFMA(pa3, ATT_PK(3), o[d0]);
;     ...
;     }
; }
.LBB0_1062:
	s_add_i32 s42, s44, 0x2000
	s_and_b32 s45, s44, 0x6000
	v_add_u32_e32 v218, s45, v132
	s_cmp_ge_i32 s34, s31
	s_cselect_b64 s[8:9], -1, 0
	s_add_i32 s98, s34, 1
	s_setprio 1
	s_waitcnt lgkmcnt(6)
	v_mfma_f32_32x32x16_bf16 v[64:79], v[154:157], v[92:95], v[220:235]
	ds_read_b64_tr_b16 v[186:187], v218
	ds_read_b64_tr_b16 v[188:189], v218 offset:512
	ds_read_b64_tr_b16 v[190:191], v218 offset:1024
	ds_read_b64_tr_b16 v[192:193], v218 offset:1536
	v_mfma_f32_32x32x16_bf16 v[48:63], v[158:161], v[92:95], v[220:235]
	ds_read_b64_tr_b16 v[194:195], v218 offset:2048
	ds_read_b64_tr_b16 v[196:197], v218 offset:2560
	ds_read_b64_tr_b16 v[198:199], v218 offset:3072
	ds_read_b64_tr_b16 v[200:201], v218 offset:3584
	s_waitcnt lgkmcnt(12)
	v_mfma_f32_32x32x16_bf16 v[64:79], v[162:165], v[88:91], v[64:79]
	ds_read_b64_tr_b16 v[202:203], v218 offset:4096
	ds_read_b64_tr_b16 v[204:205], v218 offset:4608
	ds_read_b64_tr_b16 v[206:207], v218 offset:5120
	ds_read_b64_tr_b16 v[208:209], v218 offset:5632
	v_mfma_f32_32x32x16_bf16 v[48:63], v[166:169], v[88:91], v[48:63]
	ds_read_b64_tr_b16 v[210:211], v218 offset:6144
	ds_read_b64_tr_b16 v[212:213], v218 offset:6656
	ds_read_b64_tr_b16 v[214:215], v218 offset:7168
	ds_read_b64_tr_b16 v[216:217], v218 offset:7680
	s_waitcnt lgkmcnt(15)
	v_mfma_f32_32x32x16_bf16 v[64:79], v[170:173], v[84:87], v[64:79]
	s_lshr_b32 s45, s98, 2
	v_lshrrev_b32_e32 v219, s45, v129
	v_and_b32_e32 v219, 1, v219
	v_cmp_eq_u32_e32 vcc, 1, v219
	s_cmp_ge_i32 s98, s31
	v_mfma_f32_32x32x16_bf16 v[48:63], v[174:177], v[84:87], v[48:63]
	s_nop 0
	v_cndmask_b32_e32 v219, v126, v128, vcc
	s_cselect_b64 vcc, 0, -1
	s_nop 1
	v_cndmask_b32_e32 v219, 0, v219, vcc
	s_waitcnt lgkmcnt(15)
	v_mfma_f32_32x32x16_bf16 v[64:79], v[178:181], v[80:83], v[64:79]
	v_add_f32_e32 v220, v0, v219
	v_add_f32_e32 v221, v1, v219
	v_add_f32_e32 v222, v2, v219
	v_add_f32_e32 v223, v3, v219
	v_add_f32_e32 v224, v4, v219
	v_add_f32_e32 v225, v5, v219
	v_mfma_f32_32x32x16_bf16 v[48:63], v[182:185], v[80:83], v[48:63]
	v_add_f32_e32 v226, v6, v219
	v_add_f32_e32 v227, v7, v219
	v_add_f32_e32 v228, v8, v219
	v_add_f32_e32 v229, v9, v219
	v_add_f32_e32 v230, v10, v219
	v_add_f32_e32 v231, v11, v219
	s_waitcnt lgkmcnt(14)
	v_mfma_f32_32x32x16_bf16 v[16:31], v[108:111], v[186:189], v[16:31]
	v_add_f32_e32 v232, v12, v219
	v_add_f32_e32 v233, v13, v219
	v_add_f32_e32 v234, v14, v219
	v_add_f32_e32 v235, v15, v219
	s_waitcnt lgkmcnt(12)
	v_mfma_f32_32x32x16_bf16 v[16:31], v[104:107], v[190:193], v[16:31]
	s_waitcnt lgkmcnt(10)
	v_mfma_f32_32x32x16_bf16 v[16:31], v[100:103], v[194:197], v[16:31]
	s_waitcnt lgkmcnt(8)
	v_mfma_f32_32x32x16_bf16 v[16:31], v[96:99], v[198:201], v[16:31]
	s_waitcnt lgkmcnt(6)
	v_mfma_f32_32x32x16_bf16 v[32:47], v[108:111], v[202:205], v[32:47]
	s_waitcnt lgkmcnt(4)
	v_mfma_f32_32x32x16_bf16 v[32:47], v[104:107], v[206:209], v[32:47]
	s_waitcnt lgkmcnt(2)
	v_mfma_f32_32x32x16_bf16 v[32:47], v[100:103], v[210:213], v[32:47]
	s_waitcnt lgkmcnt(0)
	v_mfma_f32_32x32x16_bf16 v[32:47], v[96:99], v[214:217], v[32:47]
	s_setprio 0
	s_barrier
	s_add_i32 s98, s42, 0x2000
	s_and_b32 s45, s98, 0x6000
	v_add_u32_e32 v133, s45, v130
	ds_read_b128 v[154:157], v133
	ds_read_b128 v[158:161], v133 offset:512
	ds_read_b128 v[162:165], v133 offset:2048
	ds_read_b128 v[166:169], v133 offset:2560
	ds_read_b128 v[170:173], v133 offset:4096
	ds_read_b128 v[174:177], v133 offset:4608
	ds_read_b128 v[178:181], v133 offset:6144
	ds_read_b128 v[182:185], v133 offset:6656
	s_and_b64 vcc, exec, s[8:9]
	s_cbranch_vccnz .Lmb1_bias
.Lmb1_exp:
	v_exp_f32_e32 v64, v64
	v_exp_f32_e32 v48, v48
	v_exp_f32_e32 v65, v65
	v_exp_f32_e32 v49, v49
	v_exp_f32_e32 v66, v66
	v_exp_f32_e32 v50, v50
	v_exp_f32_e32 v67, v67
	v_exp_f32_e32 v51, v51
	v_add_f32_e32 v96, v48, v64
	v_exp_f32_e32 v68, v68
	v_exp_f32_e32 v52, v52
	v_add_f32_e32 v96, 0, v96
	v_add_f32_e32 v97, v49, v65
	v_exp_f32_e32 v69, v69
	v_exp_f32_e32 v53, v53
	v_add_f32_e32 v96, v97, v96
	v_add_f32_e32 v97, v50, v66
	v_exp_f32_e32 v70, v70
	v_exp_f32_e32 v54, v54
	v_add_f32_e32 v96, v97, v96
	v_add_f32_e32 v97, v51, v67
	v_exp_f32_e32 v71, v71
	v_exp_f32_e32 v55, v55
	v_add_f32_e32 v96, v97, v96
	v_add_f32_e32 v97, v52, v68
	v_exp_f32_e32 v72, v72
	v_exp_f32_e32 v56, v56
	v_add_f32_e32 v96, v97, v96
	v_add_f32_e32 v97, v53, v69
	v_exp_f32_e32 v73, v73
	v_exp_f32_e32 v57, v57
	v_add_f32_e32 v96, v97, v96
	v_add_f32_e32 v97, v54, v70
	v_exp_f32_e32 v74, v74
	v_exp_f32_e32 v58, v58
	v_add_f32_e32 v96, v97, v96
	v_add_f32_e32 v97, v55, v71
	v_exp_f32_e32 v75, v75
	v_exp_f32_e32 v59, v59
	v_add_f32_e32 v96, v97, v96
	v_add_f32_e32 v97, v56, v72
	v_exp_f32_e32 v76, v76
	v_exp_f32_e32 v60, v60
	v_add_f32_e32 v96, v97, v96
	v_add_f32_e32 v97, v57, v73
	v_exp_f32_e32 v77, v77
	v_exp_f32_e32 v61, v61
	v_add_f32_e32 v96, v97, v96
	v_add_f32_e32 v97, v58, v74
	v_exp_f32_e32 v78, v78
	v_exp_f32_e32 v62, v62
	v_add_f32_e32 v96, v97, v96
	v_add_f32_e32 v97, v59, v75
	v_exp_f32_e32 v79, v79
	v_exp_f32_e32 v63, v63
	v_add_f32_e32 v96, v97, v96
	v_add_f32_e32 v97, v60, v76
	v_add_f32_e32 v96, v97, v96
	v_add_f32_e32 v97, v61, v77
	v_add_f32_e32 v96, v97, v96
	v_add_f32_e32 v97, v62, v78
	v_add_f32_e32 v96, v97, v96
	v_add_f32_e32 v97, v63, v79
	v_add_f32_e32 v96, v97, v96
	v_add_f32_e32 v131, v131, v96
	v_cvt_pk_bf16_f32 v108, v64, v65
	v_cvt_pk_bf16_f32 v109, v66, v67
	v_cvt_pk_bf16_f32 v110, v68, v69
	v_cvt_pk_bf16_f32 v111, v70, v71
	v_cvt_pk_bf16_f32 v104, v72, v73
	v_cvt_pk_bf16_f32 v105, v74, v75
	v_cvt_pk_bf16_f32 v106, v76, v77
	v_cvt_pk_bf16_f32 v107, v78, v79
	v_cvt_pk_bf16_f32 v100, v48, v49
	v_cvt_pk_bf16_f32 v101, v50, v51
	v_cvt_pk_bf16_f32 v102, v52, v53
	v_cvt_pk_bf16_f32 v103, v54, v55
	v_cvt_pk_bf16_f32 v96, v56, v57
	v_cvt_pk_bf16_f32 v97, v58, v59
	v_cvt_pk_bf16_f32 v98, v60, v61
	v_cvt_pk_bf16_f32 v99, v62, v63
	s_add_i32 s34, s34, 1
	v_lshl_add_u64 v[114:115], v[114:115], 0, s[22:23]
	v_subrev_u32_e32 v112, 64, v112
	v_lshl_add_u64 v[116:117], v[116:117], 0, s[22:23]
	s_cmp_eq_u32 s43, 2
	s_cbranch_scc0 .Lmb1_b2o
	s_waitcnt vmcnt(2)
.Lmb1_b2:
	s_barrier
	s_cmp_lg_u32 s37, s36
	s_cbranch_scc0 .LBB0_1075
	s_mov_b32 s44, s42
	s_add_i32 s37, s34, -1
	s_mov_b32 s43, 0
	s_cmp_ge_u32 s37, s30
	s_cbranch_scc0 .LBB0_1059
	s_branch .LBB0_1060
.Lmb1_bias:
	s_lshr_b32 s44, s34, 2
	s_cmp_eq_u32 s44, s91
	s_cselect_b64 s[8:9], -1, 0
	s_lshl_b32 s44, 1, s44
	v_and_b32_e32 v96, s44, v129
	v_cmp_ne_u32_e32 vcc, 0, v96
	s_or_b64 vcc, s[8:9], vcc
	s_nop 0
	v_cndmask_b32_e32 v96, v127, v112, vcc
	v_lshl_add_u32 v96, v96, 2, 0
	v_add_u32_e32 v104, 0x1d000, v96
	ds_read2_b32 v[96:97], v104 offset0:58 offset1:59
	ds_read2_b32 v[98:99], v104 offset0:26 offset1:27
	ds_read2_b32 v[100:101], v104 offset0:56 offset1:57
	s_waitcnt lgkmcnt(2)
	v_pk_add_f32 v[64:65], v[64:65], v[96:97] op_sel:[0,1] op_sel_hi:[1,0]
	ds_read2_b32 v[96:97], v104 offset0:24 offset1:25
	s_waitcnt lgkmcnt(2)
	v_pk_add_f32 v[48:49], v[48:49], v[98:99] op_sel:[0,1] op_sel_hi:[1,0]
	ds_read2_b32 v[98:99], v104 offset0:50 offset1:51
	s_waitcnt lgkmcnt(2)
	v_pk_add_f32 v[66:67], v[66:67], v[100:101] op_sel:[0,1] op_sel_hi:[1,0]
	ds_read2_b32 v[100:101], v104 offset0:18 offset1:19
	s_waitcnt lgkmcnt(1)
	v_pk_add_f32 v[68:69], v[68:69], v[98:99] op_sel:[0,1] op_sel_hi:[1,0]
	ds_read2_b32 v[98:99], v104 offset0:16 offset1:17
	s_waitcnt lgkmcnt(1)
	v_pk_add_f32 v[52:53], v[52:53], v[100:101] op_sel:[0,1] op_sel_hi:[1,0]
	ds_read2_b32 v[100:101], v104 offset0:42 offset1:43
	v_pk_add_f32 v[50:51], v[50:51], v[96:97] op_sel:[0,1] op_sel_hi:[1,0]
	ds_read2_b32 v[96:97], v104 offset0:48 offset1:49
	s_waitcnt lgkmcnt(1)
	v_pk_add_f32 v[72:73], v[72:73], v[100:101] op_sel:[0,1] op_sel_hi:[1,0]
	ds_read2_b32 v[100:101], v104 offset0:8 offset1:9
	s_waitcnt lgkmcnt(1)
	v_pk_add_f32 v[70:71], v[70:71], v[96:97] op_sel:[0,1] op_sel_hi:[1,0]
	ds_read2_b32 v[96:97], v104 offset0:10 offset1:11
	v_pk_add_f32 v[54:55], v[54:55], v[98:99] op_sel:[0,1] op_sel_hi:[1,0]
	ds_read2_b32 v[98:99], v104 offset0:40 offset1:41
	s_waitcnt lgkmcnt(2)
	v_pk_add_f32 v[58:59], v[58:59], v[100:101] op_sel:[0,1] op_sel_hi:[1,0]
	s_waitcnt lgkmcnt(1)
	v_pk_add_f32 v[56:57], v[56:57], v[96:97] op_sel:[0,1] op_sel_hi:[1,0]
	ds_read2_b32 v[96:97], v104 offset0:34 offset1:35
	s_waitcnt lgkmcnt(1)
	v_pk_add_f32 v[74:75], v[74:75], v[98:99] op_sel:[0,1] op_sel_hi:[1,0]
	ds_read2_b32 v[98:99], v104 offset0:2 offset1:3
	ds_read2_b32 v[102:103], v104 offset0:32 offset1:33
	ds_read2_b32 v[104:105], v104 offset1:1
	s_waitcnt lgkmcnt(3)
	v_pk_add_f32 v[76:77], v[76:77], v[96:97] op_sel:[0,1] op_sel_hi:[1,0]
	s_waitcnt lgkmcnt(2)
	v_pk_add_f32 v[60:61], v[60:61], v[98:99] op_sel:[0,1] op_sel_hi:[1,0]
	s_waitcnt lgkmcnt(1)
	v_pk_add_f32 v[78:79], v[78:79], v[102:103] op_sel:[0,1] op_sel_hi:[1,0]
	s_waitcnt lgkmcnt(0)
	v_pk_add_f32 v[62:63], v[62:63], v[104:105] op_sel:[0,1] op_sel_hi:[1,0]
	s_branch .Lmb1_exp
.Lmb1_b2o:
	s_cmp_eq_u32 s43, 1
	s_cbranch_scc1 .Lmb1_b2w1
	s_waitcnt vmcnt(0)
	s_branch .Lmb1_b2
.Lmb1_b2w1:
	s_waitcnt vmcnt(1)
	s_branch .Lmb1_b2

.LBB0_2382:
	s_nop 8
	v_exp_f32_e32 v56, v32
	s_nop 0
	v_exp_f32_e32 v57, v16
	v_exp_f32_e32 v112, v33
	v_exp_f32_e32 v16, v17
	v_exp_f32_e32 v58, v18
	v_add_f32_e32 v17, v57, v56
	v_exp_f32_e32 v18, v19
	v_pk_add_f32 v[32:33], v[16:17], v[112:113]
	v_exp_f32_e32 v17, v34
	v_pk_add_f32 v[32:33], v[32:33], v[32:33] op_sel_hi:[0,1]
	v_exp_f32_e32 v32, v35
	v_lshlrev_b32_e32 v59, 1, v52
	v_add_f32_e32 v19, v58, v17
	s_mov_b64 s[10:11], 0x80000
	v_pk_add_f32 v[34:35], v[18:19], v[32:33]
	v_exp_f32_e32 v19, v36
	v_pk_add_f32 v[34:35], v[34:35], v[34:35] op_sel_hi:[0,1]
	v_exp_f32_e32 v33, v20
	v_exp_f32_e32 v34, v37
	v_exp_f32_e32 v20, v21
	v_lshl_add_u64 v[114:115], v[48:49], 0, s[10:11]
	v_add_f32_e32 v21, v33, v19
	s_add_i32 s10, s86, s42
	v_pk_add_f32 v[36:37], v[20:21], v[34:35]
	v_exp_f32_e32 v21, v38
	v_pk_add_f32 v[36:37], v[36:37], v[36:37] op_sel_hi:[0,1]
	v_exp_f32_e32 v35, v22
	v_exp_f32_e32 v36, v39
	v_exp_f32_e32 v22, v23
	v_cvt_pk_bf16_f32 v100, v57, v16
	v_add_f32_e32 v23, v35, v21
	s_waitcnt vmcnt(0) lgkmcnt(0)
	s_barrier
	v_pk_add_f32 v[38:39], v[22:23], v[36:37]
	v_exp_f32_e32 v23, v40
	v_pk_add_f32 v[38:39], v[38:39], v[38:39] op_sel_hi:[0,1]
	v_exp_f32_e32 v37, v24
	v_exp_f32_e32 v38, v41
	v_exp_f32_e32 v24, v25
	v_and_b32_e32 v25, 32, v59
	v_add_u32_e32 v59, s89, v25
	v_add_f32_e32 v25, v37, v23
	v_pk_add_f32 v[40:41], v[24:25], v[38:39]
	v_exp_f32_e32 v25, v42
	v_pk_add_f32 v[40:41], v[40:41], v[40:41] op_sel_hi:[0,1]
	v_exp_f32_e32 v39, v26
	v_exp_f32_e32 v40, v43
	v_exp_f32_e32 v26, v27
	v_lshrrev_b32_e32 v27, 2, v52
	v_and_or_b32 v52, v27, 3, v55
	v_add_f32_e32 v27, v39, v25
	v_pk_add_f32 v[42:43], v[26:27], v[40:41]
	v_exp_f32_e32 v27, v44
	v_pk_add_f32 v[42:43], v[42:43], v[42:43] op_sel_hi:[0,1]
	v_exp_f32_e32 v41, v28
	v_exp_f32_e32 v42, v45
	v_exp_f32_e32 v28, v29
	v_add_u32_e32 v16, s10, v54
	v_add_f32_e32 v29, v41, v27
	s_lshl_b32 s28, s93, 2
	v_pk_add_f32 v[44:45], v[28:29], v[42:43]
	v_exp_f32_e32 v29, v46
	v_pk_add_f32 v[44:45], v[44:45], v[44:45] op_sel_hi:[0,1]
	v_exp_f32_e32 v43, v30
	v_exp_f32_e32 v44, v47
	v_exp_f32_e32 v30, v31
	v_lshlrev_b32_e32 v52, 6, v52
	v_add_f32_e32 v31, v43, v29
	v_cvt_pk_bf16_f32 v108, v56, v112
	v_pk_add_f32 v[46:47], v[30:31], v[44:45]
	v_sub_u32_e32 v112, v16, v55
	v_add_f32_e32 v31, v46, v47
	v_mov_b32_e32 v16, 0
	s_add_i32 s29, s28, -2
	s_mov_b32 s30, 1
	s_add_i32 s31, s28, 4
	v_add3_u32 v132, v59, v53, v52
	s_mov_b32 s43, 0
	v_add_f32_e32 v131, 0, v31
	v_cvt_pk_bf16_f32 v109, v17, v32
	v_cvt_pk_bf16_f32 v110, v19, v34
	v_cvt_pk_bf16_f32 v111, v21, v36
	v_cvt_pk_bf16_f32 v104, v23, v38
	v_cvt_pk_bf16_f32 v105, v25, v40
	v_cvt_pk_bf16_f32 v106, v27, v42
	v_cvt_pk_bf16_f32 v107, v29, v44
	v_cvt_pk_bf16_f32 v101, v58, v18
	v_cvt_pk_bf16_f32 v102, v33, v20
	v_cvt_pk_bf16_f32 v103, v35, v22
	v_cvt_pk_bf16_f32 v96, v37, v24
	v_cvt_pk_bf16_f32 v97, v39, v26
	v_cvt_pk_bf16_f32 v98, v41, v28
	v_cvt_pk_bf16_f32 v99, v43, v30
	s_or_b32 s34, s28, 2
	v_lshl_add_u64 v[116:117], v[50:51], 0, s[24:25]
	v_mov_b32_e32 v17, v16
	v_mov_b32_e32 v18, v16
	v_mov_b32_e32 v19, v16
	v_mov_b32_e32 v20, v16
	v_mov_b32_e32 v21, v16
	v_mov_b32_e32 v22, v16
	v_mov_b32_e32 v23, v16
	v_mov_b32_e32 v24, v16
	v_mov_b32_e32 v25, v16
	v_mov_b32_e32 v26, v16
	v_mov_b32_e32 v27, v16
	v_mov_b32_e32 v28, v16
	v_mov_b32_e32 v29, v16
	v_mov_b32_e32 v30, v16
	v_mov_b32_e32 v31, v16
	v_mov_b32_e32 v32, v16
	v_mov_b32_e32 v33, v16
	v_mov_b32_e32 v34, v16
	v_mov_b32_e32 v35, v16
	v_mov_b32_e32 v36, v16
	v_mov_b32_e32 v37, v16
	v_mov_b32_e32 v38, v16
	v_mov_b32_e32 v39, v16
	v_mov_b32_e32 v40, v16
	v_mov_b32_e32 v41, v16
	v_mov_b32_e32 v42, v16
	v_mov_b32_e32 v43, v16
	v_mov_b32_e32 v44, v16
	v_mov_b32_e32 v45, v16
	v_mov_b32_e32 v46, v16
	v_mov_b32_e32 v47, v16
	s_add_i32 s36, s43, 0x2000
	s_and_b32 s42, s36, 0x6000
	v_add_u32_e32 v133, s42, v130
	ds_read_b128 v[154:157], v133
	ds_read_b128 v[158:161], v133 offset:512
	ds_read_b128 v[162:165], v133 offset:2048
	ds_read_b128 v[166:169], v133 offset:2560
	ds_read_b128 v[170:173], v133 offset:4096
	ds_read_b128 v[174:177], v133 offset:4608
	ds_read_b128 v[178:181], v133 offset:6144
	ds_read_b128 v[182:185], v133 offset:6656
	s_lshr_b32 s42, s30, 2
	v_lshrrev_b32_e32 v219, s42, v129
	v_and_b32_e32 v219, 1, v219
	v_cmp_eq_u32_e32 vcc, 1, v219
	s_cmp_ge_i32 s30, s29
	s_nop 0
	v_cndmask_b32_e32 v219, v126, v128, vcc
	s_cselect_b64 vcc, 0, -1
	s_nop 1
	v_cndmask_b32_e32 v219, 0, v219, vcc
	v_add_f32_e32 v220, v0, v219
	v_add_f32_e32 v221, v1, v219
	v_add_f32_e32 v222, v2, v219
	v_add_f32_e32 v223, v3, v219
	v_add_f32_e32 v224, v4, v219
	v_add_f32_e32 v225, v5, v219
	v_add_f32_e32 v226, v6, v219
	v_add_f32_e32 v227, v7, v219
	v_add_f32_e32 v228, v8, v219
	v_add_f32_e32 v229, v9, v219
	v_add_f32_e32 v230, v10, v219
	v_add_f32_e32 v231, v11, v219
	v_add_f32_e32 v232, v12, v219
	v_add_f32_e32 v233, v13, v219
	v_add_f32_e32 v234, v14, v219
	v_add_f32_e32 v235, v15, v219
	s_add_i32 s35, s30, -1
	s_cmp_ge_u32 s35, s28
	s_mov_b32 s37, 0
	s_cbranch_scc1 .LBB0_2384

; #define ATT_LAS __attribute__((address_space(3)))
; #define ATT_MFMA(a, b, c) __builtin_amdgcn_mfma_f32_32x32x16_bf16((a), (b), (c), 0, 0, 0)
; __device__ __forceinline__ void qkt(f32x16& p0, f32x16& p1, lds_cptr kb, const bf16x8* qr, const f32x16& z) {
; #pragma unroll
;     for (int d0 = 0; d0 < 4; ++d0) {
;         const bf16x8 b0 = *(const ATT_LAS bf16x8*)(kb + d0 * 2048);
;         const bf16x8 b1 = *(const ATT_LAS bf16x8*)(kb + d0 * 2048 + 512);
;         if (d0 == 0) { p0 = ATT_MFMA(b0, qr[0], z); p1 = ATT_MFMA(b1, qr[0], z); }
;         else { p0 = ATT_MFMA(b0, qr[d0], p0); p1 = ATT_MFMA(b1, qr[d0], p1); } }
; }
; __device__ __forceinline__ void pv(f32x16* o, int vb, bf16x8 pa0, bf16x8 pa1, bf16x8 pa2, bf16x8 pa3) {
; #pragma unroll
;     for (int d0 = 0; d0 < 2; ++d0) { s16x4 lo[4], hi[4];
; #pragma unroll
;         for (int ks = 0; ks < 4; ++ks) {
;             asm volatile("ds_read_b64_tr_b16 %0,%1 offset:%c2" : "=&v"(lo[ks]) : "v"(vb), "i"(d0 * 4096 + ks * 1024) : "memory");
;             asm volatile("ds_read_b64_tr_b16 %0,%1 offset:%c2" : "=&v"(hi[ks]) : "v"(vb), "i"(d0 * 4096 + ks * 1024 + 512) : "memory"); }
;         asm volatile("s_waitcnt lgkmcnt(0)" ::: "memory"); __builtin_amdgcn_sched_barrier(0);
;     ...
;         o[d0] = ATT_MFMA(pa0, ATT_PK(0), o[d0]);
;         o[d0] = ATT_MFMA(pa1, ATT_PK(1), o[d0]);
;         o[d0] = ATT_MFMA(pa2, ATT_PK(2), o[d0]);
;         o[d0] = ATT_MFMA(pa3, ATT_PK(3), o[d0]);
;     ...
;     }
; }
.LBB0_2386:
	s_add_i32 s36, s43, 0x2000
	s_and_b32 s42, s43, 0x6000
	v_add_u32_e32 v218, s42, v132
	s_cmp_ge_i32 s30, s29
	s_cselect_b64 s[10:11], -1, 0
	s_add_i32 s98, s30, 1
	s_setprio 1
	s_waitcnt lgkmcnt(6)
	v_mfma_f32_32x32x16_bf16 v[64:79], v[154:157], v[92:95], v[220:235]
	ds_read_b64_tr_b16 v[186:187], v218
	ds_read_b64_tr_b16 v[188:189], v218 offset:512
	ds_read_b64_tr_b16 v[190:191], v218 offset:1024
	ds_read_b64_tr_b16 v[192:193], v218 offset:1536
	v_mfma_f32_32x32x16_bf16 v[48:63], v[158:161], v[92:95], v[220:235]
	ds_read_b64_tr_b16 v[194:195], v218 offset:2048
	ds_read_b64_tr_b16 v[196:197], v218 offset:2560
	ds_read_b64_tr_b16 v[198:199], v218 offset:3072
	ds_read_b64_tr_b16 v[200:201], v218 offset:3584
	s_waitcnt lgkmcnt(12)
	v_mfma_f32_32x32x16_bf16 v[64:79], v[162:165], v[88:91], v[64:79]
	ds_read_b64_tr_b16 v[202:203], v218 offset:4096
	ds_read_b64_tr_b16 v[204:205], v218 offset:4608
	ds_read_b64_tr_b16 v[206:207], v218 offset:5120
	ds_read_b64_tr_b16 v[208:209], v218 offset:5632
	v_mfma_f32_32x32x16_bf16 v[48:63], v[166:169], v[88:91], v[48:63]
	ds_read_b64_tr_b16 v[210:211], v218 offset:6144
	ds_read_b64_tr_b16 v[212:213], v218 offset:6656
	ds_read_b64_tr_b16 v[214:215], v218 offset:7168
	ds_read_b64_tr_b16 v[216:217], v218 offset:7680
	s_waitcnt lgkmcnt(15)
	v_mfma_f32_32x32x16_bf16 v[64:79], v[170:173], v[84:87], v[64:79]
	s_lshr_b32 s42, s98, 2
	v_lshrrev_b32_e32 v219, s42, v129
	v_and_b32_e32 v219, 1, v219
	v_cmp_eq_u32_e32 vcc, 1, v219
	s_cmp_ge_i32 s98, s29
	v_mfma_f32_32x32x16_bf16 v[48:63], v[174:177], v[84:87], v[48:63]
	s_nop 0
	v_cndmask_b32_e32 v219, v126, v128, vcc
	s_cselect_b64 vcc, 0, -1
	s_nop 1
	v_cndmask_b32_e32 v219, 0, v219, vcc
	s_waitcnt lgkmcnt(15)
	v_mfma_f32_32x32x16_bf16 v[64:79], v[178:181], v[80:83], v[64:79]
	v_add_f32_e32 v220, v0, v219
	v_add_f32_e32 v221, v1, v219
	v_add_f32_e32 v222, v2, v219
	v_add_f32_e32 v223, v3, v219
	v_add_f32_e32 v224, v4, v219
	v_add_f32_e32 v225, v5, v219
	v_mfma_f32_32x32x16_bf16 v[48:63], v[182:185], v[80:83], v[48:63]
	v_add_f32_e32 v226, v6, v219
	v_add_f32_e32 v227, v7, v219
	v_add_f32_e32 v228, v8, v219
	v_add_f32_e32 v229, v9, v219
	v_add_f32_e32 v230, v10, v219
	v_add_f32_e32 v231, v11, v219
	s_waitcnt lgkmcnt(14)
	v_mfma_f32_32x32x16_bf16 v[16:31], v[108:111], v[186:189], v[16:31]
	v_add_f32_e32 v232, v12, v219
	v_add_f32_e32 v233, v13, v219
	v_add_f32_e32 v234, v14, v219
	v_add_f32_e32 v235, v15, v219
	s_waitcnt lgkmcnt(12)
	v_mfma_f32_32x32x16_bf16 v[16:31], v[104:107], v[190:193], v[16:31]
	s_waitcnt lgkmcnt(10)
	v_mfma_f32_32x32x16_bf16 v[16:31], v[100:103], v[194:197], v[16:31]
	s_waitcnt lgkmcnt(8)
	v_mfma_f32_32x32x16_bf16 v[16:31], v[96:99], v[198:201], v[16:31]
	s_waitcnt lgkmcnt(6)
	v_mfma_f32_32x32x16_bf16 v[32:47], v[108:111], v[202:205], v[32:47]
	s_waitcnt lgkmcnt(4)
	v_mfma_f32_32x32x16_bf16 v[32:47], v[104:107], v[206:209], v[32:47]
	s_waitcnt lgkmcnt(2)
	v_mfma_f32_32x32x16_bf16 v[32:47], v[100:103], v[210:213], v[32:47]
	s_waitcnt lgkmcnt(0)
	v_mfma_f32_32x32x16_bf16 v[32:47], v[96:99], v[214:217], v[32:47]
	s_setprio 0
	s_barrier
	s_add_i32 s98, s36, 0x2000
	s_and_b32 s42, s98, 0x6000
	v_add_u32_e32 v133, s42, v130
	ds_read_b128 v[154:157], v133
	ds_read_b128 v[158:161], v133 offset:512
	ds_read_b128 v[162:165], v133 offset:2048
	ds_read_b128 v[166:169], v133 offset:2560
	ds_read_b128 v[170:173], v133 offset:4096
	ds_read_b128 v[174:177], v133 offset:4608
	ds_read_b128 v[178:181], v133 offset:6144
	ds_read_b128 v[182:185], v133 offset:6656
	s_and_b64 vcc, exec, s[10:11]
	s_cbranch_vccnz .Lmb3_bias
.Lmb3_exp:
	v_exp_f32_e32 v64, v64
	v_exp_f32_e32 v48, v48
	v_exp_f32_e32 v65, v65
	v_exp_f32_e32 v49, v49
	v_exp_f32_e32 v66, v66
	v_exp_f32_e32 v50, v50
	v_exp_f32_e32 v67, v67
	v_exp_f32_e32 v51, v51
	v_add_f32_e32 v96, v48, v64
	v_exp_f32_e32 v68, v68
	v_exp_f32_e32 v52, v52
	v_add_f32_e32 v96, 0, v96
	v_add_f32_e32 v97, v49, v65
	v_exp_f32_e32 v69, v69
	v_exp_f32_e32 v53, v53
	v_add_f32_e32 v96, v97, v96
	v_add_f32_e32 v97, v50, v66
	v_exp_f32_e32 v70, v70
	v_exp_f32_e32 v54, v54
	v_add_f32_e32 v96, v97, v96
	v_add_f32_e32 v97, v51, v67
	v_exp_f32_e32 v71, v71
	v_exp_f32_e32 v55, v55
	v_add_f32_e32 v96, v97, v96
	v_add_f32_e32 v97, v52, v68
	v_exp_f32_e32 v72, v72
	v_exp_f32_e32 v56, v56
	v_add_f32_e32 v96, v97, v96
	v_add_f32_e32 v97, v53, v69
	v_exp_f32_e32 v73, v73
	v_exp_f32_e32 v57, v57
	v_add_f32_e32 v96, v97, v96
	v_add_f32_e32 v97, v54, v70
	v_exp_f32_e32 v74, v74
	v_exp_f32_e32 v58, v58
	v_add_f32_e32 v96, v97, v96
	v_add_f32_e32 v97, v55, v71
	v_exp_f32_e32 v75, v75
	v_exp_f32_e32 v59, v59
	v_add_f32_e32 v96, v97, v96
	v_add_f32_e32 v97, v56, v72
	v_exp_f32_e32 v76, v76
	v_exp_f32_e32 v60, v60
	v_add_f32_e32 v96, v97, v96
	v_add_f32_e32 v97, v57, v73
	v_exp_f32_e32 v77, v77
	v_exp_f32_e32 v61, v61
	v_add_f32_e32 v96, v97, v96
	v_add_f32_e32 v97, v58, v74
	v_exp_f32_e32 v78, v78
	v_exp_f32_e32 v62, v62
	v_add_f32_e32 v96, v97, v96
	v_add_f32_e32 v97, v59, v75
	v_exp_f32_e32 v79, v79
	v_exp_f32_e32 v63, v63
	v_add_f32_e32 v96, v97, v96
	v_add_f32_e32 v97, v60, v76
	v_add_f32_e32 v96, v97, v96
	v_add_f32_e32 v97, v61, v77
	v_add_f32_e32 v96, v97, v96
	v_add_f32_e32 v97, v62, v78
	v_add_f32_e32 v96, v97, v96
	v_add_f32_e32 v97, v63, v79
	v_add_f32_e32 v96, v97, v96
	v_add_f32_e32 v131, v131, v96
	v_cvt_pk_bf16_f32 v108, v64, v65
	v_cvt_pk_bf16_f32 v109, v66, v67
	v_cvt_pk_bf16_f32 v110, v68, v69
	v_cvt_pk_bf16_f32 v111, v70, v71
	v_cvt_pk_bf16_f32 v104, v72, v73
	v_cvt_pk_bf16_f32 v105, v74, v75
	v_cvt_pk_bf16_f32 v106, v76, v77
	v_cvt_pk_bf16_f32 v107, v78, v79
	v_cvt_pk_bf16_f32 v100, v48, v49
	v_cvt_pk_bf16_f32 v101, v50, v51
	v_cvt_pk_bf16_f32 v102, v52, v53
	v_cvt_pk_bf16_f32 v103, v54, v55
	v_cvt_pk_bf16_f32 v96, v56, v57
	v_cvt_pk_bf16_f32 v97, v58, v59
	v_cvt_pk_bf16_f32 v98, v60, v61
	v_cvt_pk_bf16_f32 v99, v62, v63
	s_add_i32 s30, s30, 1
	v_lshl_add_u64 v[114:115], v[114:115], 0, s[20:21]
	v_subrev_u32_e32 v112, 64, v112
	v_lshl_add_u64 v[116:117], v[116:117], 0, s[20:21]
	s_cmp_eq_u32 s37, 2
	s_cbranch_scc0 .Lmb3_b2o
	s_waitcnt vmcnt(2)
.Lmb3_b2:
	s_barrier
	s_cmp_lg_u32 s35, s34
	s_cbranch_scc0 .LBB0_2399
	s_mov_b32 s43, s36
	s_add_i32 s35, s30, -1
	s_mov_b32 s37, 0
	s_cmp_ge_u32 s35, s28
	s_cbranch_scc0 .LBB0_2383
	s_branch .LBB0_2384
.Lmb3_bias:
	s_lshr_b32 s42, s30, 2
	s_cmp_eq_u32 s42, s93
	s_cselect_b64 s[10:11], -1, 0
	s_lshl_b32 s42, 1, s42
	v_and_b32_e32 v96, s42, v129
	v_cmp_ne_u32_e32 vcc, 0, v96
	s_or_b64 vcc, s[10:11], vcc
	s_nop 0
	v_cndmask_b32_e32 v96, v127, v112, vcc
	v_lshl_add_u32 v96, v96, 2, 0
	v_add_u32_e32 v104, 0x1d000, v96
	ds_read2_b32 v[96:97], v104 offset0:58 offset1:59
	ds_read2_b32 v[98:99], v104 offset0:26 offset1:27
	ds_read2_b32 v[100:101], v104 offset0:56 offset1:57
	s_waitcnt lgkmcnt(2)
	v_pk_add_f32 v[64:65], v[64:65], v[96:97] op_sel:[0,1] op_sel_hi:[1,0]
	ds_read2_b32 v[96:97], v104 offset0:24 offset1:25
	s_waitcnt lgkmcnt(2)
	v_pk_add_f32 v[48:49], v[48:49], v[98:99] op_sel:[0,1] op_sel_hi:[1,0]
	ds_read2_b32 v[98:99], v104 offset0:50 offset1:51
	s_waitcnt lgkmcnt(2)
	v_pk_add_f32 v[66:67], v[66:67], v[100:101] op_sel:[0,1] op_sel_hi:[1,0]
	ds_read2_b32 v[100:101], v104 offset0:18 offset1:19
	s_waitcnt lgkmcnt(1)
	v_pk_add_f32 v[68:69], v[68:69], v[98:99] op_sel:[0,1] op_sel_hi:[1,0]
	ds_read2_b32 v[98:99], v104 offset0:16 offset1:17
	s_waitcnt lgkmcnt(1)
	v_pk_add_f32 v[52:53], v[52:53], v[100:101] op_sel:[0,1] op_sel_hi:[1,0]
	ds_read2_b32 v[100:101], v104 offset0:42 offset1:43
	v_pk_add_f32 v[50:51], v[50:51], v[96:97] op_sel:[0,1] op_sel_hi:[1,0]
	ds_read2_b32 v[96:97], v104 offset0:48 offset1:49
	s_waitcnt lgkmcnt(1)
	v_pk_add_f32 v[72:73], v[72:73], v[100:101] op_sel:[0,1] op_sel_hi:[1,0]
	ds_read2_b32 v[100:101], v104 offset0:8 offset1:9
	s_waitcnt lgkmcnt(1)
	v_pk_add_f32 v[70:71], v[70:71], v[96:97] op_sel:[0,1] op_sel_hi:[1,0]
	ds_read2_b32 v[96:97], v104 offset0:10 offset1:11
	v_pk_add_f32 v[54:55], v[54:55], v[98:99] op_sel:[0,1] op_sel_hi:[1,0]
	ds_read2_b32 v[98:99], v104 offset0:40 offset1:41
	s_waitcnt lgkmcnt(2)
	v_pk_add_f32 v[58:59], v[58:59], v[100:101] op_sel:[0,1] op_sel_hi:[1,0]
	s_waitcnt lgkmcnt(1)
	v_pk_add_f32 v[56:57], v[56:57], v[96:97] op_sel:[0,1] op_sel_hi:[1,0]
	ds_read2_b32 v[96:97], v104 offset0:34 offset1:35
	s_waitcnt lgkmcnt(1)
	v_pk_add_f32 v[74:75], v[74:75], v[98:99] op_sel:[0,1] op_sel_hi:[1,0]
	ds_read2_b32 v[98:99], v104 offset0:2 offset1:3
	ds_read2_b32 v[102:103], v104 offset0:32 offset1:33
	ds_read2_b32 v[104:105], v104 offset1:1
	s_waitcnt lgkmcnt(3)
	v_pk_add_f32 v[76:77], v[76:77], v[96:97] op_sel:[0,1] op_sel_hi:[1,0]
	s_waitcnt lgkmcnt(2)
	v_pk_add_f32 v[60:61], v[60:61], v[98:99] op_sel:[0,1] op_sel_hi:[1,0]
	s_waitcnt lgkmcnt(1)
	v_pk_add_f32 v[78:79], v[78:79], v[102:103] op_sel:[0,1] op_sel_hi:[1,0]
	s_waitcnt lgkmcnt(0)
	v_pk_add_f32 v[62:63], v[62:63], v[104:105] op_sel:[0,1] op_sel_hi:[1,0]
	s_branch .Lmb3_exp
.Lmb3_b2o:
	s_cmp_eq_u32 s37, 1
	s_cbranch_scc1 .Lmb3_b2w1
	s_waitcnt vmcnt(0)
	s_branch .Lmb3_b2

; __global__ void __launch_bounds__(NWAVES * 64, 2) fwd_megakernel(Args args) {
	.amdhsa_kernel _Z14fwd_megakernel4Args
		.amdhsa_group_segment_fixed_size 0
		.amdhsa_private_segment_fixed_size 0
		.amdhsa_kernarg_size 400
		.amdhsa_user_sgpr_count 2
		.amdhsa_user_sgpr_dispatch_ptr 0
		.amdhsa_user_sgpr_queue_ptr 0
		.amdhsa_user_sgpr_kernarg_segment_ptr 1
		.amdhsa_user_sgpr_dispatch_id 0
		.amdhsa_user_sgpr_kernarg_preload_length 0
		.amdhsa_user_sgpr_kernarg_preload_offset 0
		.amdhsa_user_sgpr_private_segment_size 0
		.amdhsa_uses_dynamic_stack 0
		.amdhsa_enable_private_segment 0
		.amdhsa_system_sgpr_workgroup_id_x 1
		.amdhsa_system_sgpr_workgroup_id_y 0
		.amdhsa_system_sgpr_workgroup_id_z 0
		.amdhsa_system_sgpr_workgroup_info 0
		.amdhsa_system_vgpr_workitem_id 2
		.amdhsa_next_free_vgpr 255
		.amdhsa_next_free_sgpr 100
		.amdhsa_accum_offset 256
		.amdhsa_reserve_vcc 1
		.amdhsa_float_round_mode_32 0
		.amdhsa_float_round_mode_16_64 0
		.amdhsa_float_denorm_mode_32 3
		.amdhsa_float_denorm_mode_16_64 3
		.amdhsa_dx10_clamp 1
		.amdhsa_ieee_mode 1
		.amdhsa_fp16_overflow 0
		.amdhsa_tg_split 0
		.amdhsa_exception_fp_ieee_invalid_op 0
		.amdhsa_exception_fp_denorm_src 0
		.amdhsa_exception_fp_ieee_div_zero 0
		.amdhsa_exception_fp_ieee_overflow 0
		.amdhsa_exception_fp_ieee_underflow 0
		.amdhsa_exception_fp_ieee_inexact 0
		.amdhsa_exception_int_div_zero 0
	.end_amdhsa_kernel

; __global__ void __launch_bounds__(NWAVES * 64, 2) fwd_megakernel(Args args) {
amdhsa.kernels:
  - .agpr_count:     0
    .args:
      - .offset:         0
        .size:           144
        .value_kind:     by_value
      - .offset:         144
        .size:           4
        .value_kind:     hidden_block_count_x
      - .offset:         148
        .size:           4
        .value_kind:     hidden_block_count_y
      - .offset:         152
        .size:           4
        .value_kind:     hidden_block_count_z
      - .offset:         156
        .size:           2
        .value_kind:     hidden_group_size_x
      - .offset:         158
        .size:           2
        .value_kind:     hidden_group_size_y
      - .offset:         160
        .size:           2
        .value_kind:     hidden_group_size_z
      - .offset:         162
        .size:           2
        .value_kind:     hidden_remainder_x
      - .offset:         164
        .size:           2
        .value_kind:     hidden_remainder_y
      - .offset:         166
        .size:           2
        .value_kind:     hidden_remainder_z
      - .offset:         184
        .size:           8
        .value_kind:     hidden_global_offset_x
      - .offset:         192
        .size:           8
        .value_kind:     hidden_global_offset_y
      - .offset:         200
        .size:           8
        .value_kind:     hidden_global_offset_z
      - .offset:         208
        .size:           2
        .value_kind:     hidden_grid_dims
      - .offset:         232
        .size:           8
        .value_kind:     hidden_multigrid_sync_arg
      - .offset:         264
        .size:           4
        .value_kind:     hidden_dynamic_lds_size
    .group_segment_fixed_size: 0
    .kernarg_segment_align: 8
    .kernarg_segment_size: 400
    .language:       OpenCL C
    .language_version:
      - 2
      - 0
    .max_flat_workgroup_size: 512
    .name:           _Z14fwd_megakernel4Args
    .private_segment_fixed_size: 0
    .sgpr_count:     106
    .sgpr_spill_count: 8
    .symbol:         _Z14fwd_megakernel4Args.kd
    .uniform_work_group_size: 1
    .uses_dynamic_stack: false
    .vgpr_count:     255
    .vgpr_spill_count: 0
    .wavefront_size: 64
